# EpiGate: conv-weight loads ordered by first use with counted waits (vmcnt(3) before the n=0 batch, vmcnt(0) before n=1), side stores of rows 0/1 deferred behind the first group's compute; rest as v65
# speedup vs baseline: 1.0043x; 1.0043x over previous
;     __device__ __forceinline__ void operator()(const f32x4 (&acc)[2][2][4][2], const Unit& u, int wr, int wc, int fr, int fq) const {
;         const int ch0 = u.pn * 128 + wc * 32 + 8 * fq;
;         f32x4 w0[2], w1[2], w2[2];
; #pragma unroll
;         for (int n = 0; n < 2; ++n) { w0[n] = *(const f32x4*)(cw + ch0 + 4 * n); w1[n] = *(const f32x4*)(cw + ldh + ch0 + 4 * n); w2[n] = *(const f32x4*)(cw + 2 * ldh + ch0 + 4 * n); }
;         const bool f1 = fr >= 1, f2 = fr >= 2;
; #pragma unroll
;         for (int ai = 0; ai < 2; ++ai) {
;             const int blk = u.pm * 4 + ai * 2 + wr;
; #pragma unroll
;             for (int m = 0; m < 4; ++m) {
;                 const size_t row = (size_t)(u.pm * BM + ai * HALF + wr * 64 + m * 16 + fr);
;                 float hg[8];
; #pragma unroll
;                 for (int n = 0; n < 2; ++n)
; #pragma unroll
;                     for (int i = 0; i < 4; ++i) {
;                         const float cur = acc[ai][0][m][n][i], prv = (m > 0) ? acc[ai][0][m > 0 ? m - 1 : 0][n][i] : cur;
;                         const float r1c = dpp_ror1(cur), r1p = dpp_ror1(prv), r2c = dpp_ror2(cur), r2p = dpp_ror2(prv);
;                         const float tm1 = f1 ? r1c : r1p, tm2 = f2 ? r2c : r2p;
;                         const float cv = w0[n][i] * tm2 + w1[n][i] * tm1 + w2[n][i] * cur;
;                         hg[4 * n + i] = cv * sigmoidf_(cv) * acc[ai][1][m][n][i];
;                     }
;                 if (m == 0 && fr < 2) {
;                     const f32x4 a0 = acc[ai][0][0][0], a1 = acc[ai][0][0][1], v0 = acc[ai][1][0][0], v1 = acc[ai][1][0][1];
;                     u32x4 wa, wv; wa.x = cvt_pk_bf16(a0[0], a0[1]); wa.y = cvt_pk_bf16(a0[2], a0[3]); wa.z = cvt_pk_bf16(a1[0], a1[1]); wa.w = cvt_pk_bf16(a1[2], a1[3]);
;                     wv.x = cvt_pk_bf16(v0[0], v0[1]); wv.y = cvt_pk_bf16(v0[2], v0[3]); wv.z = cvt_pk_bf16(v1[0], v1[1]); wv.w = cvt_pk_bf16(v1[2], v1[3]);
;                     *(u32x4*)(side + ((size_t)blk * 6 + 2 + fr) * ldh + ch0) = wa; *(u32x4*)(side + ((size_t)blk * 6 + 4 + fr) * ldh + ch0) = wv;
;                 } else {
;                     u32x4 w; w.x = cvt_pk_bf16(hg[0], hg[1]); w.y = cvt_pk_bf16(hg[2], hg[3]); w.z = cvt_pk_bf16(hg[4], hg[5]); w.w = cvt_pk_bf16(hg[6], hg[7]);
;                     *(u32x4*)(HG + row * ldh + ch0) = w;
;                 }
.LBB0_713:
	v_lshl_or_b32 v70, s15, 7, v221
	v_lshlrev_b32_e32 v71, 2, v70
	global_load_dwordx4 v[192:195], v71, s[58:59]
	global_load_dwordx4 v[232:235], v71, s[56:57]
	global_load_dwordx4 v[224:227], v71, s[52:53]
	global_load_dwordx4 v[196:199], v71, s[58:59] offset:16
	global_load_dwordx4 v[236:239], v71, s[56:57] offset:16
	global_load_dwordx4 v[228:231], v71, s[52:53] offset:16
	s_mov_b32 s65, 0x100000
	v_and_b32_e32 v72, 15, v161
	v_cmp_eq_u32_e64 s[16:17], 15, v72
	v_lshlrev_b32_e32 v188, 1, v70
	v_mov_b32_e32 v189, 0
	v_lshl_add_u32 v73, s14, 8, v161
	v_mad_u64_u32 v[170:171], vcc, v73, s92, v[188:189]
	s_lshl_b32 s14, s14, 2
	s_add_i32 s14, s14, s8
	s_mul_i32 s14, s14, 6
	v_add_u32_e32 v73, s14, v72
	v_lshl_add_u64 v[170:171], s[50:51], 0, v[170:171]
	v_mad_u64_u32 v[190:191], vcc, v73, s92, v[188:189]
	s_mov_b64 s[22:23], exec
	s_mov_b32 s14, 0xbfb8aa3b
	s_mov_b32 s15, 0xbfb8aa3b
	s_mov_b32 s24, 1.0
	s_mov_b32 s25, 1.0
	v_lshl_add_u64 v[190:191], s[48:49], 0, v[190:191]
	v_cvt_pk_bf16_f32 v154, v142, v143
	v_cvt_pk_bf16_f32 v155, v144, v145
	v_cvt_pk_bf16_f32 v156, v130, v131
	v_cvt_pk_bf16_f32 v157, v132, v133
	v_cvt_pk_bf16_f32 v204, v150, v151
	v_cvt_pk_bf16_f32 v205, v152, v153
	v_cvt_pk_bf16_f32 v206, v146, v147
	v_cvt_pk_bf16_f32 v207, v148, v149
	v_add_co_u32_e32 v188, vcc, 0xac00, v190
	v_addc_co_u32_e32 v189, vcc, 0, v191, vcc
	v_add_co_u32_e32 v208, vcc, 0x15800, v190
	v_addc_co_u32_e32 v209, vcc, 0, v191, vcc
	s_waitcnt vmcnt(3)
	v_pk_mul_f32 v[70:71], v[192:193], v[142:143]
	v_pk_mul_f32 v[72:73], v[194:195], v[144:145]
	v_fmac_f32_dpp v70, v142, v232 row_ror:1 row_mask:0xf bank_mask:0xf
	v_fmac_f32_dpp v71, v143, v233 row_ror:1 row_mask:0xf bank_mask:0xf
	v_fmac_f32_dpp v72, v144, v234 row_ror:1 row_mask:0xf bank_mask:0xf
	v_fmac_f32_dpp v73, v145, v235 row_ror:1 row_mask:0xf bank_mask:0xf
	v_fmac_f32_dpp v70, v142, v224 row_ror:2 row_mask:0xf bank_mask:0xf
	v_fmac_f32_dpp v71, v143, v225 row_ror:2 row_mask:0xf bank_mask:0xf
	v_fmac_f32_dpp v72, v144, v226 row_ror:2 row_mask:0xf bank_mask:0xf
	v_fmac_f32_dpp v73, v145, v227 row_ror:2 row_mask:0xf bank_mask:0xf
	v_pk_mul_f32 v[200:201], v[70:71], s[14:15]
	v_pk_mul_f32 v[202:203], v[72:73], s[14:15]
	v_exp_f32_e32 v200, v200
	v_exp_f32_e32 v201, v201
	v_exp_f32_e32 v202, v202
	v_exp_f32_e32 v203, v203
	v_pk_add_f32 v[200:201], v[200:201], s[24:25]
	v_pk_add_f32 v[202:203], v[202:203], s[24:25]
	v_rcp_f32_e32 v200, v200
	v_rcp_f32_e32 v201, v201
	v_rcp_f32_e32 v202, v202
	v_rcp_f32_e32 v203, v203
	v_pk_mul_f32 v[70:71], v[70:71], v[200:201]
	v_pk_mul_f32 v[72:73], v[72:73], v[202:203]
	v_pk_mul_f32 v[150:151], v[150:151], v[70:71]
	v_pk_mul_f32 v[152:153], v[152:153], v[72:73]
	s_waitcnt vmcnt(0)
	v_pk_mul_f32 v[70:71], v[196:197], v[130:131]
	v_pk_mul_f32 v[72:73], v[198:199], v[132:133]
	v_fmac_f32_dpp v70, v130, v236 row_ror:1 row_mask:0xf bank_mask:0xf
	v_fmac_f32_dpp v71, v131, v237 row_ror:1 row_mask:0xf bank_mask:0xf
	v_fmac_f32_dpp v72, v132, v238 row_ror:1 row_mask:0xf bank_mask:0xf
	v_fmac_f32_dpp v73, v133, v239 row_ror:1 row_mask:0xf bank_mask:0xf
	v_fmac_f32_dpp v70, v130, v228 row_ror:2 row_mask:0xf bank_mask:0xf
	v_fmac_f32_dpp v71, v131, v229 row_ror:2 row_mask:0xf bank_mask:0xf
	v_fmac_f32_dpp v72, v132, v230 row_ror:2 row_mask:0xf bank_mask:0xf
	v_fmac_f32_dpp v73, v133, v231 row_ror:2 row_mask:0xf bank_mask:0xf
	v_pk_mul_f32 v[200:201], v[70:71], s[14:15]
	v_pk_mul_f32 v[202:203], v[72:73], s[14:15]
	v_exp_f32_e32 v200, v200
	v_exp_f32_e32 v201, v201
	v_exp_f32_e32 v202, v202
	v_exp_f32_e32 v203, v203
	v_pk_add_f32 v[200:201], v[200:201], s[24:25]
	v_pk_add_f32 v[202:203], v[202:203], s[24:25]
	v_rcp_f32_e32 v200, v200
	v_rcp_f32_e32 v201, v201
	v_rcp_f32_e32 v202, v202
	v_rcp_f32_e32 v203, v203
	v_pk_mul_f32 v[70:71], v[70:71], v[200:201]
	v_pk_mul_f32 v[72:73], v[72:73], v[202:203]
	v_pk_mul_f32 v[146:147], v[146:147], v[70:71]
	v_pk_mul_f32 v[148:149], v[148:149], v[72:73]
	s_andn2_b64 exec, s[22:23], s[40:41]
	global_store_dwordx4 v[188:189], v[154:157], off
	global_store_dwordx4 v[208:209], v[204:207], off
	s_mov_b64 exec, s[22:23]
	v_cvt_pk_bf16_f32 v150, v150, v151
	v_cvt_pk_bf16_f32 v151, v152, v153
	v_cvt_pk_bf16_f32 v152, v146, v147
	v_cvt_pk_bf16_f32 v153, v148, v149
	s_and_b64 exec, s[22:23], s[40:41]
	global_store_dwordx4 v[170:171], v[150:153], off
	s_mov_b64 exec, s[22:23]
	v_cndmask_b32_e64 v200, v138, v142, s[16:17]
	v_cndmask_b32_e64 v201, v139, v143, s[16:17]
	v_cndmask_b32_e64 v202, v140, v144, s[16:17]
	v_cndmask_b32_e64 v203, v141, v145, s[16:17]
	v_cndmask_b32_e64 v204, v138, v142, s[42:43]
	v_cndmask_b32_e64 v205, v139, v143, s[42:43]
	v_cndmask_b32_e64 v206, v140, v144, s[42:43]
	v_cndmask_b32_e64 v207, v141, v145, s[42:43]
	v_pk_mul_f32 v[70:71], v[192:193], v[138:139]
	v_pk_mul_f32 v[72:73], v[194:195], v[140:141]
	v_fmac_f32_dpp v70, v200, v232 row_ror:1 row_mask:0xf bank_mask:0xf
	v_fmac_f32_dpp v71, v201, v233 row_ror:1 row_mask:0xf bank_mask:0xf
	v_fmac_f32_dpp v72, v202, v234 row_ror:1 row_mask:0xf bank_mask:0xf
	v_fmac_f32_dpp v73, v203, v235 row_ror:1 row_mask:0xf bank_mask:0xf
	v_fmac_f32_dpp v70, v204, v224 row_ror:2 row_mask:0xf bank_mask:0xf
	v_fmac_f32_dpp v71, v205, v225 row_ror:2 row_mask:0xf bank_mask:0xf
	v_fmac_f32_dpp v72, v206, v226 row_ror:2 row_mask:0xf bank_mask:0xf
	v_fmac_f32_dpp v73, v207, v227 row_ror:2 row_mask:0xf bank_mask:0xf
	v_pk_mul_f32 v[200:201], v[70:71], s[14:15]
	v_pk_mul_f32 v[202:203], v[72:73], s[14:15]
	v_exp_f32_e32 v200, v200
	v_exp_f32_e32 v201, v201
	v_exp_f32_e32 v202, v202
	v_exp_f32_e32 v203, v203
	v_pk_add_f32 v[200:201], v[200:201], s[24:25]
	v_pk_add_f32 v[202:203], v[202:203], s[24:25]
; __device__ __forceinline__ unsigned cvt_pk_bf16(float lo, float hi) { unsigned r; asm volatile("v_cvt_pk_bf16_f32 %0, %1, %2" : "=v"(r) : "v"(lo), "v"(hi)); return r; }
; __device__ __forceinline__ float sigmoidf_(float x) { return __builtin_amdgcn_rcpf(1.0f + __expf(-x)); }
; __device__ __forceinline__ float dpp_ror1(float x) { return __int_as_float(__builtin_amdgcn_update_dpp(0, __float_as_int(x), 0x121, 0xF, 0xF, true)); }
;     __device__ __forceinline__ void operator()(const f32x4 (&acc)[2][2][4][2], const Unit& u, int wr, int wc, int fr, int fq) const {
;     ...
;             for (int m = 0; m < 4; ++m) {
;                 const size_t row = (size_t)(u.pm * BM + ai * HALF + wr * 64 + m * 16 + fr);
;                 float hg[8];
; #pragma unroll
;                 for (int n = 0; n < 2; ++n)
; #pragma unroll
;                     for (int i = 0; i < 4; ++i) {
;                         const float cur = acc[ai][0][m][n][i], prv = (m > 0) ? acc[ai][0][m > 0 ? m - 1 : 0][n][i] : cur;
;                         const float r1c = dpp_ror1(cur), r1p = dpp_ror1(prv), r2c = dpp_ror2(cur), r2p = dpp_ror2(prv);
;                         const float tm1 = f1 ? r1c : r1p, tm2 = f2 ? r2c : r2p;
;                         const float cv = w0[n][i] * tm2 + w1[n][i] * tm1 + w2[n][i] * cur;
;                         hg[4 * n + i] = cv * sigmoidf_(cv) * acc[ai][1][m][n][i];
;                     }
;                 if (m == 0 && fr < 2) {
;                     const f32x4 a0 = acc[ai][0][0][0], a1 = acc[ai][0][0][1], v0 = acc[ai][1][0][0], v1 = acc[ai][1][0][1];
;                     u32x4 wa, wv; wa.x = cvt_pk_bf16(a0[0], a0[1]); wa.y = cvt_pk_bf16(a0[2], a0[3]); wa.z = cvt_pk_bf16(a1[0], a1[1]); wa.w = cvt_pk_bf16(a1[2], a1[3]);
;                     wv.x = cvt_pk_bf16(v0[0], v0[1]); wv.y = cvt_pk_bf16(v0[2], v0[3]); wv.z = cvt_pk_bf16(v1[0], v1[1]); wv.w = cvt_pk_bf16(v1[2], v1[3]);
;                     *(u32x4*)(side + ((size_t)blk * 6 + 2 + fr) * ldh + ch0) = wa; *(u32x4*)(side + ((size_t)blk * 6 + 4 + fr) * ldh + ch0) = wv;
;                 } else {
;                     u32x4 w; w.x = cvt_pk_bf16(hg[0], hg[1]); w.y = cvt_pk_bf16(hg[2], hg[3]); w.z = cvt_pk_bf16(hg[4], hg[5]); w.w = cvt_pk_bf16(hg[6], hg[7]);
;                     *(u32x4*)(HG + row * ldh + ch0) = w;
;                 }
	v_rcp_f32_e32 v200, v200
	v_rcp_f32_e32 v201, v201
	v_rcp_f32_e32 v202, v202
	v_rcp_f32_e32 v203, v203
	v_pk_mul_f32 v[70:71], v[70:71], v[200:201]
	v_pk_mul_f32 v[72:73], v[72:73], v[202:203]
	v_pk_mul_f32 v[134:135], v[134:135], v[70:71]
	v_pk_mul_f32 v[136:137], v[136:137], v[72:73]
	v_cndmask_b32_e64 v200, v126, v130, s[16:17]
	v_cndmask_b32_e64 v201, v127, v131, s[16:17]
	v_cndmask_b32_e64 v202, v128, v132, s[16:17]
	v_cndmask_b32_e64 v203, v129, v133, s[16:17]
	v_cndmask_b32_e64 v204, v126, v130, s[42:43]
	v_cndmask_b32_e64 v205, v127, v131, s[42:43]
	v_cndmask_b32_e64 v206, v128, v132, s[42:43]
	v_cndmask_b32_e64 v207, v129, v133, s[42:43]
	v_pk_mul_f32 v[70:71], v[196:197], v[126:127]
	v_pk_mul_f32 v[72:73], v[198:199], v[128:129]
	v_fmac_f32_dpp v70, v200, v236 row_ror:1 row_mask:0xf bank_mask:0xf
	v_fmac_f32_dpp v71, v201, v237 row_ror:1 row_mask:0xf bank_mask:0xf
	v_fmac_f32_dpp v72, v202, v238 row_ror:1 row_mask:0xf bank_mask:0xf
	v_fmac_f32_dpp v73, v203, v239 row_ror:1 row_mask:0xf bank_mask:0xf
	v_fmac_f32_dpp v70, v204, v228 row_ror:2 row_mask:0xf bank_mask:0xf
	v_fmac_f32_dpp v71, v205, v229 row_ror:2 row_mask:0xf bank_mask:0xf
	v_fmac_f32_dpp v72, v206, v230 row_ror:2 row_mask:0xf bank_mask:0xf
	v_fmac_f32_dpp v73, v207, v231 row_ror:2 row_mask:0xf bank_mask:0xf
	v_pk_mul_f32 v[200:201], v[70:71], s[14:15]
	v_pk_mul_f32 v[202:203], v[72:73], s[14:15]
	v_exp_f32_e32 v200, v200
	v_exp_f32_e32 v201, v201
	v_exp_f32_e32 v202, v202
	v_exp_f32_e32 v203, v203
	v_pk_add_f32 v[200:201], v[200:201], s[24:25]
	v_pk_add_f32 v[202:203], v[202:203], s[24:25]
	v_rcp_f32_e32 v200, v200
	v_rcp_f32_e32 v201, v201
	v_rcp_f32_e32 v202, v202
	v_rcp_f32_e32 v203, v203
	v_pk_mul_f32 v[70:71], v[70:71], v[200:201]
	v_pk_mul_f32 v[72:73], v[72:73], v[202:203]
	v_pk_mul_f32 v[122:123], v[122:123], v[70:71]
	v_pk_mul_f32 v[124:125], v[124:125], v[72:73]
	v_cvt_pk_bf16_f32 v134, v134, v135
	v_cvt_pk_bf16_f32 v135, v136, v137
	v_cvt_pk_bf16_f32 v136, v122, v123
	v_cvt_pk_bf16_f32 v137, v124, v125
	v_add_co_u32_e32 v170, vcc, 0x56000, v170
	v_addc_co_u32_e32 v171, vcc, 0, v171, vcc
	global_store_dwordx4 v[170:171], v[134:137], off
	v_cndmask_b32_e64 v200, v118, v138, s[16:17]
	v_cndmask_b32_e64 v201, v119, v139, s[16:17]
	v_cndmask_b32_e64 v202, v120, v140, s[16:17]
	v_cndmask_b32_e64 v203, v121, v141, s[16:17]
	v_cndmask_b32_e64 v204, v118, v138, s[42:43]
	v_cndmask_b32_e64 v205, v119, v139, s[42:43]
	v_cndmask_b32_e64 v206, v120, v140, s[42:43]
	v_cndmask_b32_e64 v207, v121, v141, s[42:43]
	v_pk_mul_f32 v[70:71], v[192:193], v[118:119]
	v_pk_mul_f32 v[72:73], v[194:195], v[120:121]
	v_fmac_f32_dpp v70, v200, v232 row_ror:1 row_mask:0xf bank_mask:0xf
	v_fmac_f32_dpp v71, v201, v233 row_ror:1 row_mask:0xf bank_mask:0xf
	v_fmac_f32_dpp v72, v202, v234 row_ror:1 row_mask:0xf bank_mask:0xf
	v_fmac_f32_dpp v73, v203, v235 row_ror:1 row_mask:0xf bank_mask:0xf
	v_fmac_f32_dpp v70, v204, v224 row_ror:2 row_mask:0xf bank_mask:0xf
	v_fmac_f32_dpp v71, v205, v225 row_ror:2 row_mask:0xf bank_mask:0xf
	v_fmac_f32_dpp v72, v206, v226 row_ror:2 row_mask:0xf bank_mask:0xf
	v_fmac_f32_dpp v73, v207, v227 row_ror:2 row_mask:0xf bank_mask:0xf
	v_pk_mul_f32 v[200:201], v[70:71], s[14:15]
	v_pk_mul_f32 v[202:203], v[72:73], s[14:15]
	v_exp_f32_e32 v200, v200
	v_exp_f32_e32 v201, v201
	v_exp_f32_e32 v202, v202
	v_exp_f32_e32 v203, v203
	v_pk_add_f32 v[200:201], v[200:201], s[24:25]
	v_pk_add_f32 v[202:203], v[202:203], s[24:25]
	v_rcp_f32_e32 v200, v200
	v_rcp_f32_e32 v201, v201
	v_rcp_f32_e32 v202, v202
	v_rcp_f32_e32 v203, v203
	v_pk_mul_f32 v[70:71], v[70:71], v[200:201]
	v_pk_mul_f32 v[72:73], v[72:73], v[202:203]
	v_pk_mul_f32 v[114:115], v[114:115], v[70:71]
	v_pk_mul_f32 v[116:117], v[116:117], v[72:73]
	v_cndmask_b32_e64 v200, v110, v126, s[16:17]
	v_cndmask_b32_e64 v201, v111, v127, s[16:17]
	v_cndmask_b32_e64 v202, v112, v128, s[16:17]
	v_cndmask_b32_e64 v203, v113, v129, s[16:17]
	v_cndmask_b32_e64 v204, v110, v126, s[42:43]
	v_cndmask_b32_e64 v205, v111, v127, s[42:43]
	v_cndmask_b32_e64 v206, v112, v128, s[42:43]
	v_cndmask_b32_e64 v207, v113, v129, s[42:43]
	v_pk_mul_f32 v[70:71], v[196:197], v[110:111]
	v_pk_mul_f32 v[72:73], v[198:199], v[112:113]
	v_fmac_f32_dpp v70, v200, v236 row_ror:1 row_mask:0xf bank_mask:0xf
	v_fmac_f32_dpp v71, v201, v237 row_ror:1 row_mask:0xf bank_mask:0xf
	v_fmac_f32_dpp v72, v202, v238 row_ror:1 row_mask:0xf bank_mask:0xf
	v_fmac_f32_dpp v73, v203, v239 row_ror:1 row_mask:0xf bank_mask:0xf
	v_fmac_f32_dpp v70, v204, v228 row_ror:2 row_mask:0xf bank_mask:0xf
	v_fmac_f32_dpp v71, v205, v229 row_ror:2 row_mask:0xf bank_mask:0xf
	v_fmac_f32_dpp v72, v206, v230 row_ror:2 row_mask:0xf bank_mask:0xf
	v_fmac_f32_dpp v73, v207, v231 row_ror:2 row_mask:0xf bank_mask:0xf
	v_pk_mul_f32 v[200:201], v[70:71], s[14:15]
	v_pk_mul_f32 v[202:203], v[72:73], s[14:15]
	v_exp_f32_e32 v200, v200
	v_exp_f32_e32 v201, v201
	v_exp_f32_e32 v202, v202
	v_exp_f32_e32 v203, v203
	v_pk_add_f32 v[200:201], v[200:201], s[24:25]
	v_pk_add_f32 v[202:203], v[202:203], s[24:25]
	v_rcp_f32_e32 v200, v200
	v_rcp_f32_e32 v201, v201
	v_rcp_f32_e32 v202, v202
	v_rcp_f32_e32 v203, v203
	v_pk_mul_f32 v[70:71], v[70:71], v[200:201]
	v_pk_mul_f32 v[72:73], v[72:73], v[202:203]
	v_pk_mul_f32 v[106:107], v[106:107], v[70:71]
	v_pk_mul_f32 v[108:109], v[108:109], v[72:73]
	v_cvt_pk_bf16_f32 v114, v114, v115
	v_cvt_pk_bf16_f32 v115, v116, v117
	v_cvt_pk_bf16_f32 v116, v106, v107
	v_cvt_pk_bf16_f32 v117, v108, v109
	v_add_co_u32_e32 v170, vcc, 0x56000, v170
	v_addc_co_u32_e32 v171, vcc, 0, v171, vcc
	global_store_dwordx4 v[170:171], v[114:117], off
; __device__ __forceinline__ float sigmoidf_(float x) { return __builtin_amdgcn_rcpf(1.0f + __expf(-x)); }
;     __device__ __forceinline__ void operator()(const f32x4 (&acc)[2][2][4][2], const Unit& u, int wr, int wc, int fr, int fq) const {
;     ...
;             for (int m = 0; m < 4; ++m) {
;                 const size_t row = (size_t)(u.pm * BM + ai * HALF + wr * 64 + m * 16 + fr);
;                 float hg[8];
; #pragma unroll
;                 for (int n = 0; n < 2; ++n)
; #pragma unroll
;                     for (int i = 0; i < 4; ++i) {
;                         const float cur = acc[ai][0][m][n][i], prv = (m > 0) ? acc[ai][0][m > 0 ? m - 1 : 0][n][i] : cur;
;                         const float r1c = dpp_ror1(cur), r1p = dpp_ror1(prv), r2c = dpp_ror2(cur), r2p = dpp_ror2(prv);
;                         const float tm1 = f1 ? r1c : r1p, tm2 = f2 ? r2c : r2p;
;                         const float cv = w0[n][i] * tm2 + w1[n][i] * tm1 + w2[n][i] * cur;
;                         hg[4 * n + i] = cv * sigmoidf_(cv) * acc[ai][1][m][n][i];
;                     }
;                 if (m == 0 && fr < 2) {
;                     const f32x4 a0 = acc[ai][0][0][0], a1 = acc[ai][0][0][1], v0 = acc[ai][1][0][0], v1 = acc[ai][1][0][1];
;                     u32x4 wa, wv; wa.x = cvt_pk_bf16(a0[0], a0[1]); wa.y = cvt_pk_bf16(a0[2], a0[3]); wa.z = cvt_pk_bf16(a1[0], a1[1]); wa.w = cvt_pk_bf16(a1[2], a1[3]);
;                     wv.x = cvt_pk_bf16(v0[0], v0[1]); wv.y = cvt_pk_bf16(v0[2], v0[3]); wv.z = cvt_pk_bf16(v1[0], v1[1]); wv.w = cvt_pk_bf16(v1[2], v1[3]);
;                     *(u32x4*)(side + ((size_t)blk * 6 + 2 + fr) * ldh + ch0) = wa; *(u32x4*)(side + ((size_t)blk * 6 + 4 + fr) * ldh + ch0) = wv;
;                 } else {
;                     u32x4 w; w.x = cvt_pk_bf16(hg[0], hg[1]); w.y = cvt_pk_bf16(hg[2], hg[3]); w.z = cvt_pk_bf16(hg[4], hg[5]); w.w = cvt_pk_bf16(hg[6], hg[7]);
;                     *(u32x4*)(HG + row * ldh + ch0) = w;
;                 }
;                 if (m == 3 && fr >= 14) {
;                     const f32x4 a0 = acc[ai][0][3][0], a1 = acc[ai][0][3][1];
;                     u32x4 wa; wa.x = cvt_pk_bf16(a0[0], a0[1]); wa.y = cvt_pk_bf16(a0[2], a0[3]); wa.z = cvt_pk_bf16(a1[0], a1[1]); wa.w = cvt_pk_bf16(a1[2], a1[3]);
;                     *(u32x4*)(side + ((size_t)blk * 6 + (fr - 14)) * ldh + ch0) = wa;
;                 }
	v_cndmask_b32_e64 v200, v98, v118, s[16:17]
	v_cndmask_b32_e64 v201, v99, v119, s[16:17]
	v_cndmask_b32_e64 v202, v100, v120, s[16:17]
	v_cndmask_b32_e64 v203, v101, v121, s[16:17]
	v_cndmask_b32_e64 v204, v98, v118, s[42:43]
	v_cndmask_b32_e64 v205, v99, v119, s[42:43]
	v_cndmask_b32_e64 v206, v100, v120, s[42:43]
	v_cndmask_b32_e64 v207, v101, v121, s[42:43]
	v_pk_mul_f32 v[70:71], v[192:193], v[98:99]
	v_pk_mul_f32 v[72:73], v[194:195], v[100:101]
	v_fmac_f32_dpp v70, v200, v232 row_ror:1 row_mask:0xf bank_mask:0xf
	v_fmac_f32_dpp v71, v201, v233 row_ror:1 row_mask:0xf bank_mask:0xf
	v_fmac_f32_dpp v72, v202, v234 row_ror:1 row_mask:0xf bank_mask:0xf
	v_fmac_f32_dpp v73, v203, v235 row_ror:1 row_mask:0xf bank_mask:0xf
	v_fmac_f32_dpp v70, v204, v224 row_ror:2 row_mask:0xf bank_mask:0xf
	v_fmac_f32_dpp v71, v205, v225 row_ror:2 row_mask:0xf bank_mask:0xf
	v_fmac_f32_dpp v72, v206, v226 row_ror:2 row_mask:0xf bank_mask:0xf
	v_fmac_f32_dpp v73, v207, v227 row_ror:2 row_mask:0xf bank_mask:0xf
	v_pk_mul_f32 v[200:201], v[70:71], s[14:15]
	v_pk_mul_f32 v[202:203], v[72:73], s[14:15]
	v_exp_f32_e32 v200, v200
	v_exp_f32_e32 v201, v201
	v_exp_f32_e32 v202, v202
	v_exp_f32_e32 v203, v203
	v_pk_add_f32 v[200:201], v[200:201], s[24:25]
	v_pk_add_f32 v[202:203], v[202:203], s[24:25]
	v_rcp_f32_e32 v200, v200
	v_rcp_f32_e32 v201, v201
	v_rcp_f32_e32 v202, v202
	v_rcp_f32_e32 v203, v203
	v_pk_mul_f32 v[70:71], v[70:71], v[200:201]
	v_pk_mul_f32 v[72:73], v[72:73], v[202:203]
	v_pk_mul_f32 v[102:103], v[102:103], v[70:71]
	v_pk_mul_f32 v[104:105], v[104:105], v[72:73]
	v_cndmask_b32_e64 v200, v94, v110, s[16:17]
	v_cndmask_b32_e64 v201, v95, v111, s[16:17]
	v_cndmask_b32_e64 v202, v96, v112, s[16:17]
	v_cndmask_b32_e64 v203, v97, v113, s[16:17]
	v_cndmask_b32_e64 v204, v94, v110, s[42:43]
	v_cndmask_b32_e64 v205, v95, v111, s[42:43]
	v_cndmask_b32_e64 v206, v96, v112, s[42:43]
	v_cndmask_b32_e64 v207, v97, v113, s[42:43]
	v_pk_mul_f32 v[70:71], v[196:197], v[94:95]
	v_pk_mul_f32 v[72:73], v[198:199], v[96:97]
	v_fmac_f32_dpp v70, v200, v236 row_ror:1 row_mask:0xf bank_mask:0xf
	v_fmac_f32_dpp v71, v201, v237 row_ror:1 row_mask:0xf bank_mask:0xf
	v_fmac_f32_dpp v72, v202, v238 row_ror:1 row_mask:0xf bank_mask:0xf
	v_fmac_f32_dpp v73, v203, v239 row_ror:1 row_mask:0xf bank_mask:0xf
	v_fmac_f32_dpp v70, v204, v228 row_ror:2 row_mask:0xf bank_mask:0xf
	v_fmac_f32_dpp v71, v205, v229 row_ror:2 row_mask:0xf bank_mask:0xf
	v_fmac_f32_dpp v72, v206, v230 row_ror:2 row_mask:0xf bank_mask:0xf
	v_fmac_f32_dpp v73, v207, v231 row_ror:2 row_mask:0xf bank_mask:0xf
	v_pk_mul_f32 v[200:201], v[70:71], s[14:15]
	v_pk_mul_f32 v[202:203], v[72:73], s[14:15]
	v_exp_f32_e32 v200, v200
	v_exp_f32_e32 v201, v201
	v_exp_f32_e32 v202, v202
	v_exp_f32_e32 v203, v203
	v_pk_add_f32 v[200:201], v[200:201], s[24:25]
	v_pk_add_f32 v[202:203], v[202:203], s[24:25]
	v_rcp_f32_e32 v200, v200
	v_rcp_f32_e32 v201, v201
	v_rcp_f32_e32 v202, v202
	v_rcp_f32_e32 v203, v203
	v_pk_mul_f32 v[70:71], v[70:71], v[200:201]
	v_pk_mul_f32 v[72:73], v[72:73], v[202:203]
	v_pk_mul_f32 v[90:91], v[90:91], v[70:71]
	v_pk_mul_f32 v[92:93], v[92:93], v[72:73]
	v_cvt_pk_bf16_f32 v102, v102, v103
	v_cvt_pk_bf16_f32 v103, v104, v105
	v_cvt_pk_bf16_f32 v104, v90, v91
	v_cvt_pk_bf16_f32 v105, v92, v93
	v_add_co_u32_e32 v170, vcc, 0x56000, v170
	v_addc_co_u32_e32 v171, vcc, 0, v171, vcc
	global_store_dwordx4 v[170:171], v[102:105], off
	v_cvt_pk_bf16_f32 v154, v98, v99
	v_cvt_pk_bf16_f32 v155, v100, v101
	v_cvt_pk_bf16_f32 v156, v94, v95
	v_cvt_pk_bf16_f32 v157, v96, v97
	v_add_co_u32_e32 v188, vcc, 0xfffb4c00, v190
	v_addc_co_u32_e32 v189, vcc, -1, v191, vcc
	s_and_b64 exec, s[22:23], s[42:43]
	global_store_dwordx4 v[188:189], v[154:157], off
	s_mov_b64 exec, s[22:23]
	v_cvt_pk_bf16_f32 v154, v62, v63
	v_cvt_pk_bf16_f32 v155, v64, v65
	v_cvt_pk_bf16_f32 v156, v42, v43
	v_cvt_pk_bf16_f32 v157, v44, v45
	v_cvt_pk_bf16_f32 v204, v82, v83
	v_cvt_pk_bf16_f32 v205, v84, v85
	v_cvt_pk_bf16_f32 v206, v78, v79
	v_cvt_pk_bf16_f32 v207, v80, v81
	v_add_co_u32_e32 v188, vcc, 0x4b400, v190
	v_addc_co_u32_e32 v189, vcc, 0, v191, vcc
	v_add_co_u32_e32 v208, vcc, 0x56000, v190
	v_addc_co_u32_e32 v209, vcc, 0, v191, vcc
	v_pk_mul_f32 v[70:71], v[192:193], v[62:63]
	v_pk_mul_f32 v[72:73], v[194:195], v[64:65]
	v_fmac_f32_dpp v70, v62, v232 row_ror:1 row_mask:0xf bank_mask:0xf
	v_fmac_f32_dpp v71, v63, v233 row_ror:1 row_mask:0xf bank_mask:0xf
	v_fmac_f32_dpp v72, v64, v234 row_ror:1 row_mask:0xf bank_mask:0xf
	v_fmac_f32_dpp v73, v65, v235 row_ror:1 row_mask:0xf bank_mask:0xf
	v_fmac_f32_dpp v70, v62, v224 row_ror:2 row_mask:0xf bank_mask:0xf
	v_fmac_f32_dpp v71, v63, v225 row_ror:2 row_mask:0xf bank_mask:0xf
	v_fmac_f32_dpp v72, v64, v226 row_ror:2 row_mask:0xf bank_mask:0xf
	v_fmac_f32_dpp v73, v65, v227 row_ror:2 row_mask:0xf bank_mask:0xf
	v_pk_mul_f32 v[200:201], v[70:71], s[14:15]
	v_pk_mul_f32 v[202:203], v[72:73], s[14:15]
	v_exp_f32_e32 v200, v200
	v_exp_f32_e32 v201, v201
	v_exp_f32_e32 v202, v202
	v_exp_f32_e32 v203, v203
	v_pk_add_f32 v[200:201], v[200:201], s[24:25]
	v_pk_add_f32 v[202:203], v[202:203], s[24:25]
	v_rcp_f32_e32 v200, v200
	v_rcp_f32_e32 v201, v201
	v_rcp_f32_e32 v202, v202
	v_rcp_f32_e32 v203, v203
	v_pk_mul_f32 v[70:71], v[70:71], v[200:201]
	v_pk_mul_f32 v[72:73], v[72:73], v[202:203]
	v_pk_mul_f32 v[82:83], v[82:83], v[70:71]
	v_pk_mul_f32 v[84:85], v[84:85], v[72:73]
	v_pk_mul_f32 v[70:71], v[196:197], v[42:43]
	v_pk_mul_f32 v[72:73], v[198:199], v[44:45]
	v_fmac_f32_dpp v70, v42, v236 row_ror:1 row_mask:0xf bank_mask:0xf
	v_fmac_f32_dpp v71, v43, v237 row_ror:1 row_mask:0xf bank_mask:0xf
; __device__ __forceinline__ unsigned cvt_pk_bf16(float lo, float hi) { unsigned r; asm volatile("v_cvt_pk_bf16_f32 %0, %1, %2" : "=v"(r) : "v"(lo), "v"(hi)); return r; }
; __device__ __forceinline__ float sigmoidf_(float x) { return __builtin_amdgcn_rcpf(1.0f + __expf(-x)); }
; __device__ __forceinline__ float dpp_ror1(float x) { return __int_as_float(__builtin_amdgcn_update_dpp(0, __float_as_int(x), 0x121, 0xF, 0xF, true)); }
; __device__ __forceinline__ float dpp_ror2(float x) { return __int_as_float(__builtin_amdgcn_update_dpp(0, __float_as_int(x), 0x122, 0xF, 0xF, true)); }
;     __device__ __forceinline__ void operator()(const f32x4 (&acc)[2][2][4][2], const Unit& u, int wr, int wc, int fr, int fq) const {
;     ...
;                     for (int i = 0; i < 4; ++i) {
;                         const float cur = acc[ai][0][m][n][i], prv = (m > 0) ? acc[ai][0][m > 0 ? m - 1 : 0][n][i] : cur;
;                         const float r1c = dpp_ror1(cur), r1p = dpp_ror1(prv), r2c = dpp_ror2(cur), r2p = dpp_ror2(prv);
;                         const float tm1 = f1 ? r1c : r1p, tm2 = f2 ? r2c : r2p;
;                         const float cv = w0[n][i] * tm2 + w1[n][i] * tm1 + w2[n][i] * cur;
;                         hg[4 * n + i] = cv * sigmoidf_(cv) * acc[ai][1][m][n][i];
;                     }
;                 if (m == 0 && fr < 2) {
;                     const f32x4 a0 = acc[ai][0][0][0], a1 = acc[ai][0][0][1], v0 = acc[ai][1][0][0], v1 = acc[ai][1][0][1];
;                     u32x4 wa, wv; wa.x = cvt_pk_bf16(a0[0], a0[1]); wa.y = cvt_pk_bf16(a0[2], a0[3]); wa.z = cvt_pk_bf16(a1[0], a1[1]); wa.w = cvt_pk_bf16(a1[2], a1[3]);
;                     wv.x = cvt_pk_bf16(v0[0], v0[1]); wv.y = cvt_pk_bf16(v0[2], v0[3]); wv.z = cvt_pk_bf16(v1[0], v1[1]); wv.w = cvt_pk_bf16(v1[2], v1[3]);
;                     *(u32x4*)(side + ((size_t)blk * 6 + 2 + fr) * ldh + ch0) = wa; *(u32x4*)(side + ((size_t)blk * 6 + 4 + fr) * ldh + ch0) = wv;
;                 } else {
;                     u32x4 w; w.x = cvt_pk_bf16(hg[0], hg[1]); w.y = cvt_pk_bf16(hg[2], hg[3]); w.z = cvt_pk_bf16(hg[4], hg[5]); w.w = cvt_pk_bf16(hg[6], hg[7]);
;                     *(u32x4*)(HG + row * ldh + ch0) = w;
;                 }
	v_fmac_f32_dpp v72, v44, v238 row_ror:1 row_mask:0xf bank_mask:0xf
	v_fmac_f32_dpp v73, v45, v239 row_ror:1 row_mask:0xf bank_mask:0xf
	v_fmac_f32_dpp v70, v42, v228 row_ror:2 row_mask:0xf bank_mask:0xf
	v_fmac_f32_dpp v71, v43, v229 row_ror:2 row_mask:0xf bank_mask:0xf
	v_fmac_f32_dpp v72, v44, v230 row_ror:2 row_mask:0xf bank_mask:0xf
	v_fmac_f32_dpp v73, v45, v231 row_ror:2 row_mask:0xf bank_mask:0xf
	v_pk_mul_f32 v[200:201], v[70:71], s[14:15]
	v_pk_mul_f32 v[202:203], v[72:73], s[14:15]
	v_exp_f32_e32 v200, v200
	v_exp_f32_e32 v201, v201
	v_exp_f32_e32 v202, v202
	v_exp_f32_e32 v203, v203
	v_pk_add_f32 v[200:201], v[200:201], s[24:25]
	v_pk_add_f32 v[202:203], v[202:203], s[24:25]
	v_rcp_f32_e32 v200, v200
	v_rcp_f32_e32 v201, v201
	v_rcp_f32_e32 v202, v202
	v_rcp_f32_e32 v203, v203
	v_pk_mul_f32 v[70:71], v[70:71], v[200:201]
	v_pk_mul_f32 v[72:73], v[72:73], v[202:203]
	v_pk_mul_f32 v[78:79], v[78:79], v[70:71]
	v_pk_mul_f32 v[80:81], v[80:81], v[72:73]
	s_andn2_b64 exec, s[22:23], s[40:41]
	global_store_dwordx4 v[188:189], v[154:157], off
	global_store_dwordx4 v[208:209], v[204:207], off
	s_mov_b64 exec, s[22:23]
	v_cvt_pk_bf16_f32 v82, v82, v83
	v_cvt_pk_bf16_f32 v83, v84, v85
	v_cvt_pk_bf16_f32 v84, v78, v79
	v_cvt_pk_bf16_f32 v85, v80, v81
	v_add_co_u32_e32 v170, vcc, 0x1ae000, v170
	v_addc_co_u32_e32 v171, vcc, 0, v171, vcc
	s_and_b64 exec, s[22:23], s[40:41]
	global_store_dwordx4 v[170:171], v[82:85], off
	s_mov_b64 exec, s[22:23]
	v_cndmask_b32_e64 v200, v58, v62, s[16:17]
	v_cndmask_b32_e64 v201, v59, v63, s[16:17]
	v_cndmask_b32_e64 v202, v60, v64, s[16:17]
	v_cndmask_b32_e64 v203, v61, v65, s[16:17]
	v_cndmask_b32_e64 v204, v58, v62, s[42:43]
	v_cndmask_b32_e64 v205, v59, v63, s[42:43]
	v_cndmask_b32_e64 v206, v60, v64, s[42:43]
	v_cndmask_b32_e64 v207, v61, v65, s[42:43]
	v_pk_mul_f32 v[70:71], v[192:193], v[58:59]
	v_pk_mul_f32 v[72:73], v[194:195], v[60:61]
	v_fmac_f32_dpp v70, v200, v232 row_ror:1 row_mask:0xf bank_mask:0xf
	v_fmac_f32_dpp v71, v201, v233 row_ror:1 row_mask:0xf bank_mask:0xf
	v_fmac_f32_dpp v72, v202, v234 row_ror:1 row_mask:0xf bank_mask:0xf
	v_fmac_f32_dpp v73, v203, v235 row_ror:1 row_mask:0xf bank_mask:0xf
	v_fmac_f32_dpp v70, v204, v224 row_ror:2 row_mask:0xf bank_mask:0xf
	v_fmac_f32_dpp v71, v205, v225 row_ror:2 row_mask:0xf bank_mask:0xf
	v_fmac_f32_dpp v72, v206, v226 row_ror:2 row_mask:0xf bank_mask:0xf
	v_fmac_f32_dpp v73, v207, v227 row_ror:2 row_mask:0xf bank_mask:0xf
	v_pk_mul_f32 v[200:201], v[70:71], s[14:15]
	v_pk_mul_f32 v[202:203], v[72:73], s[14:15]
	v_exp_f32_e32 v200, v200
	v_exp_f32_e32 v201, v201
	v_exp_f32_e32 v202, v202
	v_exp_f32_e32 v203, v203
	v_pk_add_f32 v[200:201], v[200:201], s[24:25]
	v_pk_add_f32 v[202:203], v[202:203], s[24:25]
	v_rcp_f32_e32 v200, v200
	v_rcp_f32_e32 v201, v201
	v_rcp_f32_e32 v202, v202
	v_rcp_f32_e32 v203, v203
	v_pk_mul_f32 v[70:71], v[70:71], v[200:201]
	v_pk_mul_f32 v[72:73], v[72:73], v[202:203]
	v_pk_mul_f32 v[46:47], v[46:47], v[70:71]
	v_pk_mul_f32 v[48:49], v[48:49], v[72:73]
	v_cndmask_b32_e64 v200, v38, v42, s[16:17]
	v_cndmask_b32_e64 v201, v39, v43, s[16:17]
	v_cndmask_b32_e64 v202, v40, v44, s[16:17]
	v_cndmask_b32_e64 v203, v41, v45, s[16:17]
	v_cndmask_b32_e64 v204, v38, v42, s[42:43]
	v_cndmask_b32_e64 v205, v39, v43, s[42:43]
	v_cndmask_b32_e64 v206, v40, v44, s[42:43]
	v_cndmask_b32_e64 v207, v41, v45, s[42:43]
	v_pk_mul_f32 v[70:71], v[196:197], v[38:39]
	v_pk_mul_f32 v[72:73], v[198:199], v[40:41]
	v_fmac_f32_dpp v70, v200, v236 row_ror:1 row_mask:0xf bank_mask:0xf
	v_fmac_f32_dpp v71, v201, v237 row_ror:1 row_mask:0xf bank_mask:0xf
	v_fmac_f32_dpp v72, v202, v238 row_ror:1 row_mask:0xf bank_mask:0xf
	v_fmac_f32_dpp v73, v203, v239 row_ror:1 row_mask:0xf bank_mask:0xf
	v_fmac_f32_dpp v70, v204, v228 row_ror:2 row_mask:0xf bank_mask:0xf
	v_fmac_f32_dpp v71, v205, v229 row_ror:2 row_mask:0xf bank_mask:0xf
	v_fmac_f32_dpp v72, v206, v230 row_ror:2 row_mask:0xf bank_mask:0xf
	v_fmac_f32_dpp v73, v207, v231 row_ror:2 row_mask:0xf bank_mask:0xf
	v_pk_mul_f32 v[200:201], v[70:71], s[14:15]
	v_pk_mul_f32 v[202:203], v[72:73], s[14:15]
	v_exp_f32_e32 v200, v200
	v_exp_f32_e32 v201, v201
	v_exp_f32_e32 v202, v202
	v_exp_f32_e32 v203, v203
	v_pk_add_f32 v[200:201], v[200:201], s[24:25]
	v_pk_add_f32 v[202:203], v[202:203], s[24:25]
	v_rcp_f32_e32 v200, v200
	v_rcp_f32_e32 v201, v201
	v_rcp_f32_e32 v202, v202
	v_rcp_f32_e32 v203, v203
	v_pk_mul_f32 v[70:71], v[70:71], v[200:201]
	v_pk_mul_f32 v[72:73], v[72:73], v[202:203]
	v_pk_mul_f32 v[34:35], v[34:35], v[70:71]
	v_pk_mul_f32 v[36:37], v[36:37], v[72:73]
	v_cvt_pk_bf16_f32 v46, v46, v47
	v_cvt_pk_bf16_f32 v47, v48, v49
	v_cvt_pk_bf16_f32 v48, v34, v35
	v_cvt_pk_bf16_f32 v49, v36, v37
	v_add_co_u32_e32 v170, vcc, 0x56000, v170
	v_addc_co_u32_e32 v171, vcc, 0, v171, vcc
	global_store_dwordx4 v[170:171], v[46:49], off
	v_cndmask_b32_e64 v200, v30, v58, s[16:17]
	v_cndmask_b32_e64 v201, v31, v59, s[16:17]
	v_cndmask_b32_e64 v202, v32, v60, s[16:17]
	v_cndmask_b32_e64 v203, v33, v61, s[16:17]
	v_cndmask_b32_e64 v204, v30, v58, s[42:43]
	v_cndmask_b32_e64 v205, v31, v59, s[42:43]
	v_cndmask_b32_e64 v206, v32, v60, s[42:43]
	v_cndmask_b32_e64 v207, v33, v61, s[42:43]
	v_pk_mul_f32 v[70:71], v[192:193], v[30:31]
	v_pk_mul_f32 v[72:73], v[194:195], v[32:33]
	v_fmac_f32_dpp v70, v200, v232 row_ror:1 row_mask:0xf bank_mask:0xf
	v_fmac_f32_dpp v71, v201, v233 row_ror:1 row_mask:0xf bank_mask:0xf
	v_fmac_f32_dpp v72, v202, v234 row_ror:1 row_mask:0xf bank_mask:0xf
	v_fmac_f32_dpp v73, v203, v235 row_ror:1 row_mask:0xf bank_mask:0xf
	v_fmac_f32_dpp v70, v204, v224 row_ror:2 row_mask:0xf bank_mask:0xf
;     __device__ __forceinline__ void operator()(const f32x4 (&acc)[2][2][4][2], const Unit& u, int wr, int wc, int fr, int fq) const {
;     ...
;                     for (int i = 0; i < 4; ++i) {
;                         const float cur = acc[ai][0][m][n][i], prv = (m > 0) ? acc[ai][0][m > 0 ? m - 1 : 0][n][i] : cur;
;                         const float r1c = dpp_ror1(cur), r1p = dpp_ror1(prv), r2c = dpp_ror2(cur), r2p = dpp_ror2(prv);
;                         const float tm1 = f1 ? r1c : r1p, tm2 = f2 ? r2c : r2p;
;                         const float cv = w0[n][i] * tm2 + w1[n][i] * tm1 + w2[n][i] * cur;
;                         hg[4 * n + i] = cv * sigmoidf_(cv) * acc[ai][1][m][n][i];
;                     }
;                 if (m == 0 && fr < 2) {
;                     const f32x4 a0 = acc[ai][0][0][0], a1 = acc[ai][0][0][1], v0 = acc[ai][1][0][0], v1 = acc[ai][1][0][1];
;                     u32x4 wa, wv; wa.x = cvt_pk_bf16(a0[0], a0[1]); wa.y = cvt_pk_bf16(a0[2], a0[3]); wa.z = cvt_pk_bf16(a1[0], a1[1]); wa.w = cvt_pk_bf16(a1[2], a1[3]);
;                     wv.x = cvt_pk_bf16(v0[0], v0[1]); wv.y = cvt_pk_bf16(v0[2], v0[3]); wv.z = cvt_pk_bf16(v1[0], v1[1]); wv.w = cvt_pk_bf16(v1[2], v1[3]);
;                     *(u32x4*)(side + ((size_t)blk * 6 + 2 + fr) * ldh + ch0) = wa; *(u32x4*)(side + ((size_t)blk * 6 + 4 + fr) * ldh + ch0) = wv;
;                 } else {
;                     u32x4 w; w.x = cvt_pk_bf16(hg[0], hg[1]); w.y = cvt_pk_bf16(hg[2], hg[3]); w.z = cvt_pk_bf16(hg[4], hg[5]); w.w = cvt_pk_bf16(hg[6], hg[7]);
;                     *(u32x4*)(HG + row * ldh + ch0) = w;
;                 }
;                 if (m == 3 && fr >= 14) {
;                     const f32x4 a0 = acc[ai][0][3][0], a1 = acc[ai][0][3][1];
;                     u32x4 wa; wa.x = cvt_pk_bf16(a0[0], a0[1]); wa.y = cvt_pk_bf16(a0[2], a0[3]); wa.z = cvt_pk_bf16(a1[0], a1[1]); wa.w = cvt_pk_bf16(a1[2], a1[3]);
;                     *(u32x4*)(side + ((size_t)blk * 6 + (fr - 14)) * ldh + ch0) = wa;
;                 }
; template <class Epi, class Sched, bool ALIGN_EPI = false, bool SP2 = false>
; __device__ __forceinline__ void gemm_phase(PG8_LAS unsigned char* lds, const Gemm g, const Sched& S, const Epi& E) {
;     ...
;         if constexpr (ALIGN_EPI) { if (wr == 0) PG8_BAR; }
;         if constexpr (!Epi::AFTER_DRAIN) { E(acc, cur, wr, wc, fr, fq); S.done(cur); }
	v_fmac_f32_dpp v71, v205, v225 row_ror:2 row_mask:0xf bank_mask:0xf
	v_fmac_f32_dpp v72, v206, v226 row_ror:2 row_mask:0xf bank_mask:0xf
	v_fmac_f32_dpp v73, v207, v227 row_ror:2 row_mask:0xf bank_mask:0xf
	v_pk_mul_f32 v[200:201], v[70:71], s[14:15]
	v_pk_mul_f32 v[202:203], v[72:73], s[14:15]
	v_exp_f32_e32 v200, v200
	v_exp_f32_e32 v201, v201
	v_exp_f32_e32 v202, v202
	v_exp_f32_e32 v203, v203
	v_pk_add_f32 v[200:201], v[200:201], s[24:25]
	v_pk_add_f32 v[202:203], v[202:203], s[24:25]
	v_rcp_f32_e32 v200, v200
	v_rcp_f32_e32 v201, v201
	v_rcp_f32_e32 v202, v202
	v_rcp_f32_e32 v203, v203
	v_pk_mul_f32 v[70:71], v[70:71], v[200:201]
	v_pk_mul_f32 v[72:73], v[72:73], v[202:203]
	v_pk_mul_f32 v[26:27], v[26:27], v[70:71]
	v_pk_mul_f32 v[28:29], v[28:29], v[72:73]
	v_cndmask_b32_e64 v200, v22, v38, s[16:17]
	v_cndmask_b32_e64 v201, v23, v39, s[16:17]
	v_cndmask_b32_e64 v202, v24, v40, s[16:17]
	v_cndmask_b32_e64 v203, v25, v41, s[16:17]
	v_cndmask_b32_e64 v204, v22, v38, s[42:43]
	v_cndmask_b32_e64 v205, v23, v39, s[42:43]
	v_cndmask_b32_e64 v206, v24, v40, s[42:43]
	v_cndmask_b32_e64 v207, v25, v41, s[42:43]
	v_pk_mul_f32 v[70:71], v[196:197], v[22:23]
	v_pk_mul_f32 v[72:73], v[198:199], v[24:25]
	v_fmac_f32_dpp v70, v200, v236 row_ror:1 row_mask:0xf bank_mask:0xf
	v_fmac_f32_dpp v71, v201, v237 row_ror:1 row_mask:0xf bank_mask:0xf
	v_fmac_f32_dpp v72, v202, v238 row_ror:1 row_mask:0xf bank_mask:0xf
	v_fmac_f32_dpp v73, v203, v239 row_ror:1 row_mask:0xf bank_mask:0xf
	v_fmac_f32_dpp v70, v204, v228 row_ror:2 row_mask:0xf bank_mask:0xf
	v_fmac_f32_dpp v71, v205, v229 row_ror:2 row_mask:0xf bank_mask:0xf
	v_fmac_f32_dpp v72, v206, v230 row_ror:2 row_mask:0xf bank_mask:0xf
	v_fmac_f32_dpp v73, v207, v231 row_ror:2 row_mask:0xf bank_mask:0xf
	v_pk_mul_f32 v[200:201], v[70:71], s[14:15]
	v_pk_mul_f32 v[202:203], v[72:73], s[14:15]
	v_exp_f32_e32 v200, v200
	v_exp_f32_e32 v201, v201
	v_exp_f32_e32 v202, v202
	v_exp_f32_e32 v203, v203
	v_pk_add_f32 v[200:201], v[200:201], s[24:25]
	v_pk_add_f32 v[202:203], v[202:203], s[24:25]
	v_rcp_f32_e32 v200, v200
	v_rcp_f32_e32 v201, v201
	v_rcp_f32_e32 v202, v202
	v_rcp_f32_e32 v203, v203
	v_pk_mul_f32 v[70:71], v[70:71], v[200:201]
	v_pk_mul_f32 v[72:73], v[72:73], v[202:203]
	v_pk_mul_f32 v[18:19], v[18:19], v[70:71]
	v_pk_mul_f32 v[20:21], v[20:21], v[72:73]
	v_cvt_pk_bf16_f32 v26, v26, v27
	v_cvt_pk_bf16_f32 v27, v28, v29
	v_cvt_pk_bf16_f32 v28, v18, v19
	v_cvt_pk_bf16_f32 v29, v20, v21
	v_add_co_u32_e32 v170, vcc, 0x56000, v170
	v_addc_co_u32_e32 v171, vcc, 0, v171, vcc
	global_store_dwordx4 v[170:171], v[26:29], off
	v_cndmask_b32_e64 v200, v10, v30, s[16:17]
	v_cndmask_b32_e64 v201, v11, v31, s[16:17]
	v_cndmask_b32_e64 v202, v12, v32, s[16:17]
	v_cndmask_b32_e64 v203, v13, v33, s[16:17]
	v_cndmask_b32_e64 v204, v10, v30, s[42:43]
	v_cndmask_b32_e64 v205, v11, v31, s[42:43]
	v_cndmask_b32_e64 v206, v12, v32, s[42:43]
	v_cndmask_b32_e64 v207, v13, v33, s[42:43]
	v_pk_mul_f32 v[70:71], v[192:193], v[10:11]
	v_pk_mul_f32 v[72:73], v[194:195], v[12:13]
	v_fmac_f32_dpp v70, v200, v232 row_ror:1 row_mask:0xf bank_mask:0xf
	v_fmac_f32_dpp v71, v201, v233 row_ror:1 row_mask:0xf bank_mask:0xf
	v_fmac_f32_dpp v72, v202, v234 row_ror:1 row_mask:0xf bank_mask:0xf
	v_fmac_f32_dpp v73, v203, v235 row_ror:1 row_mask:0xf bank_mask:0xf
	v_fmac_f32_dpp v70, v204, v224 row_ror:2 row_mask:0xf bank_mask:0xf
	v_fmac_f32_dpp v71, v205, v225 row_ror:2 row_mask:0xf bank_mask:0xf
	v_fmac_f32_dpp v72, v206, v226 row_ror:2 row_mask:0xf bank_mask:0xf
	v_fmac_f32_dpp v73, v207, v227 row_ror:2 row_mask:0xf bank_mask:0xf
	v_pk_mul_f32 v[200:201], v[70:71], s[14:15]
	v_pk_mul_f32 v[202:203], v[72:73], s[14:15]
	v_exp_f32_e32 v200, v200
	v_exp_f32_e32 v201, v201
	v_exp_f32_e32 v202, v202
	v_exp_f32_e32 v203, v203
	v_pk_add_f32 v[200:201], v[200:201], s[24:25]
	v_pk_add_f32 v[202:203], v[202:203], s[24:25]
	v_rcp_f32_e32 v200, v200
	v_rcp_f32_e32 v201, v201
	v_rcp_f32_e32 v202, v202
	v_rcp_f32_e32 v203, v203
	v_pk_mul_f32 v[70:71], v[70:71], v[200:201]
	v_pk_mul_f32 v[72:73], v[72:73], v[202:203]
	v_pk_mul_f32 v[14:15], v[14:15], v[70:71]
	v_pk_mul_f32 v[16:17], v[16:17], v[72:73]
	v_cndmask_b32_e64 v200, v6, v22, s[16:17]
	v_cndmask_b32_e64 v201, v7, v23, s[16:17]
	v_cndmask_b32_e64 v202, v8, v24, s[16:17]
	v_cndmask_b32_e64 v203, v9, v25, s[16:17]
	v_cndmask_b32_e64 v204, v6, v22, s[42:43]
	v_cndmask_b32_e64 v205, v7, v23, s[42:43]
	v_cndmask_b32_e64 v206, v8, v24, s[42:43]
	v_cndmask_b32_e64 v207, v9, v25, s[42:43]
	v_pk_mul_f32 v[70:71], v[196:197], v[6:7]
	v_pk_mul_f32 v[72:73], v[198:199], v[8:9]
	v_fmac_f32_dpp v70, v200, v236 row_ror:1 row_mask:0xf bank_mask:0xf
	v_fmac_f32_dpp v71, v201, v237 row_ror:1 row_mask:0xf bank_mask:0xf
	v_fmac_f32_dpp v72, v202, v238 row_ror:1 row_mask:0xf bank_mask:0xf
	v_fmac_f32_dpp v73, v203, v239 row_ror:1 row_mask:0xf bank_mask:0xf
	v_fmac_f32_dpp v70, v204, v228 row_ror:2 row_mask:0xf bank_mask:0xf
	v_fmac_f32_dpp v71, v205, v229 row_ror:2 row_mask:0xf bank_mask:0xf
	v_fmac_f32_dpp v72, v206, v230 row_ror:2 row_mask:0xf bank_mask:0xf
	v_fmac_f32_dpp v73, v207, v231 row_ror:2 row_mask:0xf bank_mask:0xf
	v_pk_mul_f32 v[200:201], v[70:71], s[14:15]
	v_pk_mul_f32 v[202:203], v[72:73], s[14:15]
	v_exp_f32_e32 v200, v200
	v_exp_f32_e32 v201, v201
	v_exp_f32_e32 v202, v202
	v_exp_f32_e32 v203, v203
	v_pk_add_f32 v[200:201], v[200:201], s[24:25]
	v_pk_add_f32 v[202:203], v[202:203], s[24:25]
	v_rcp_f32_e32 v200, v200
	v_rcp_f32_e32 v201, v201
	v_rcp_f32_e32 v202, v202
	v_rcp_f32_e32 v203, v203
	v_pk_mul_f32 v[70:71], v[70:71], v[200:201]
	v_pk_mul_f32 v[72:73], v[72:73], v[202:203]
	v_pk_mul_f32 v[2:3], v[2:3], v[70:71]
	v_pk_mul_f32 v[4:5], v[4:5], v[72:73]
	v_cvt_pk_bf16_f32 v14, v14, v15
	v_cvt_pk_bf16_f32 v15, v16, v17
	v_cvt_pk_bf16_f32 v16, v2, v3
	v_cvt_pk_bf16_f32 v17, v4, v5
	v_add_co_u32_e32 v170, vcc, 0x56000, v170
	v_addc_co_u32_e32 v171, vcc, 0, v171, vcc
	global_store_dwordx4 v[170:171], v[14:17], off
	v_cvt_pk_bf16_f32 v154, v10, v11
	v_cvt_pk_bf16_f32 v155, v12, v13
	v_cvt_pk_bf16_f32 v156, v6, v7
	v_cvt_pk_bf16_f32 v157, v8, v9
	v_add_co_u32_e32 v188, vcc, 0xffff5400, v190
	v_addc_co_u32_e32 v189, vcc, -1, v191, vcc
	s_and_b64 exec, s[22:23], s[42:43]
	global_store_dwordx4 v[188:189], v[154:157], off
	s_mov_b64 exec, s[22:23]
	s_andn2_b64 vcc, exec, s[20:21]
	s_mov_b64 s[20:21], -1
	s_cbranch_vccnz .LBB0_699
	s_andn2_b64 vcc, exec, s[46:47]
	s_cbranch_vccnz .LBB0_698
	s_barrier
	s_branch .LBB0_698
